# F2: left-over small tiles go to blocks 128..255 instead of the blocks holding the 32-K-tile latent tiles
# speedup vs baseline: 1.0150x; 1.0150x over previous
.LBB0_46:
	v_readlane_b32 s34, v246, 40
	v_readlane_b32 s35, v246, 41
	s_waitcnt lgkmcnt(0)
	s_barrier
	s_cmp_eq_u32 s35, 0x200
	s_cbranch_scc0 .Lf2_std
	s_sub_u32 s20, s34, 0x80
	s_add_i32 s35, s34, 0x180
	s_cmp_lt_u32 s20, 0x80
	s_cselect_b32 s35, s35, 0x7fffffff
	s_branch .Lf2_nx
.Lf2_std:
	s_add_i32 s35, s34, s35
.Lf2_nx:
	v_writelane_b32 v246, s35, 40
	s_and_b32 s35, s34, 7
	s_lshl_b32 s35, s35, 16
	s_lshr_b32 s20, s34, 3
	s_or_b32 s20, s20, s35
	s_cmp_lt_u32 s34, 640
	s_cselect_b32 s20, s20, -1
	s_cmp_lt_i32 s20, 0
	s_cbranch_scc1 .LBB0_45
	s_lshr_b32 s40, s20, 16
	s_and_b32 s21, s20, 0xffff
	s_cmp_gt_u32 s21, 15
	s_cbranch_scc0 .LBB0_58
	s_lshl_b32 s24, s21, 4
	s_lshl_b32 s0, s40, 10
	s_and_b32 s24, s24, 0xfff00
	s_add_i32 s0, s0, s24
	s_bfe_u32 s2, s20, 0x10003
	s_and_b32 s1, s20, 7
	s_addk_i32 s0, 0xff00
	s_mov_b64 s[24:25], s[66:67]
	s_cbranch_execz .LBB0_59
	s_movk_i32 s20, 0x100
	s_movk_i32 s51, 0x240
	s_branch .LBB0_60
